# attention loop: one vmcnt(0) at the embedded prefetch point covers the tiles staged a half earlier; the embedded LDS staging writes no longer wait for the loads issued in the same half
# speedup vs baseline: 1.0029x; 1.0029x over previous
.LBB0_542:
	s_cmp_gt_u32 s52, s51
	s_cbranch_scc1 .Lh1_skip
	s_mul_i32 s61, s25, 0x2200
	s_and_b32 s42, s52, 2
	s_mulk_i32 s42, 0x3400
	v_add_u32_e32 v0, s42, v160
	v_add_u32_e32 v242, s61, v161
	v_add_u32_e32 v163, 0xe000, v242
	v_add_u32_e32 v242, 0xd000, v242
	ds_read_b128 v[82:85], v0 offset:13312
	ds_read_b128 v[98:101], v0 offset:19968
	ds_read_b128 v[164:167], v0 offset:13344
	ds_read_b128 v[168:171], v0 offset:20000
	ds_read2_b64 v[238:241], v242 offset0:0 offset1:2
	ds_read2_b64 v[234:237], v163 offset0:32 offset1:34
	ds_read_b128 v[172:175], v0 offset:13376
	ds_read_b128 v[176:179], v0 offset:20032
	ds_read_b128 v[180:183], v0 offset:13408
	ds_read_b128 v[184:187], v0 offset:20064
	ds_read_b128 v[188:191], v0 offset:13440
	ds_read_b128 v[192:195], v0 offset:20096
	ds_read_b128 v[196:199], v0 offset:13472
	ds_read_b128 v[220:223], v0 offset:20128
	v_exp_f32_e32 v50, v50
	v_exp_f32_e32 v51, v51
	v_exp_f32_e32 v52, v52
	v_exp_f32_e32 v53, v53
	v_exp_f32_e32 v54, v54
	v_exp_f32_e32 v55, v55
	v_exp_f32_e32 v56, v56
	v_exp_f32_e32 v57, v57
	s_waitcnt lgkmcnt(13)
	v_mfma_f32_32x32x16_bf16 v[82:97], v[82:85], v[122:125], 0
	v_cvt_pk_bf16_f32 v224, v50, v51
	v_cvt_pk_bf16_f32 v225, v52, v53
	v_cvt_pk_bf16_f32 v226, v54, v55
	v_cvt_pk_bf16_f32 v227, v56, v57
	v_exp_f32_e32 v58, v58
	v_add_f32_e32 v200, v50, v51
	s_waitcnt lgkmcnt(12)
	v_mfma_f32_32x32x16_bf16 v[98:113], v[98:101], v[122:125], 0
	v_exp_f32_e32 v59, v59
	v_exp_f32_e32 v60, v60
	v_add_f32_e32 v201, v52, v53
	v_exp_f32_e32 v61, v61
	s_waitcnt vmcnt(0)
	s_add_i32 s60, s52, 3
	s_cmp_lt_u32 s60, s48
	s_cselect_b64 s[58:59], -1, 0
	s_cmp_ge_u32 s60, s48
	s_cbranch_scc1 .Lp1a_546
	s_waitcnt vmcnt(0)
	v_lshl_add_u64 v[2:3], s[54:55], 0, v[154:155]
	v_add_co_u32_e32 v2, vcc, 0xbe09000, v2
	s_nop 1
	v_addc_co_u32_e32 v3, vcc, 0, v3, vcc
	global_load_dwordx4 v[2:5], v[2:3], off
	s_and_saveexec_b64 s[42:43], s[40:41]
	s_cbranch_execz .Lp1a_545
	v_lshl_add_u64 v[10:11], s[54:55], 0, v[152:153]
	v_add_co_u32_e32 v10, vcc, 0xbe09000, v10
	s_nop 1
	v_addc_co_u32_e32 v11, vcc, 0, v11, vcc
	global_load_dwordx4 v[10:13], v[10:11], off

.Lp1a_end:
	s_waitcnt lgkmcnt(11)
	v_mfma_f32_32x32x16_bf16 v[82:97], v[164:167], v[126:129], v[82:97]
	v_exp_f32_e32 v62, v62
	v_add_f32_e32 v200, v200, v54
	v_exp_f32_e32 v63, v63
	v_add_f32_e32 v201, v201, v55
	v_exp_f32_e32 v64, v64
	s_waitcnt lgkmcnt(10)
	v_mfma_f32_32x32x16_bf16 v[98:113], v[168:171], v[126:129], v[98:113]
	ds_read2_b64 v[164:167], v242 offset0:4 offset1:6
	ds_read2_b64 v[168:171], v163 offset0:36 offset1:38
	v_add_f32_e32 v200, v200, v56
	v_exp_f32_e32 v65, v65
	v_add_f32_e32 v201, v201, v57
	v_cvt_pk_bf16_f32 v228, v58, v59
	v_cvt_pk_bf16_f32 v229, v60, v61
	s_waitcnt lgkmcnt(11)
	v_mfma_f32_32x32x16_bf16 v[18:33], v[238:241], v[224:227], v[18:33]
	v_cvt_pk_bf16_f32 v230, v62, v63
	v_cvt_pk_bf16_f32 v231, v64, v65
	v_exp_f32_e32 v66, v66
	v_add_f32_e32 v200, v200, v58
	v_exp_f32_e32 v67, v67
	v_add_f32_e32 v201, v201, v59
	s_waitcnt lgkmcnt(10)
	v_mfma_f32_32x32x16_bf16 v[34:49], v[234:237], v[224:227], v[34:49]
	v_exp_f32_e32 v68, v68
	v_add_f32_e32 v200, v200, v60
	v_exp_f32_e32 v69, v69
	v_add_f32_e32 v201, v201, v61
	v_exp_f32_e32 v70, v70
	s_waitcnt lgkmcnt(9)
	v_mfma_f32_32x32x16_bf16 v[82:97], v[172:175], v[134:137], v[82:97]
	v_add_f32_e32 v200, v200, v62
	v_exp_f32_e32 v71, v71
	v_add_f32_e32 v201, v201, v63
	v_exp_f32_e32 v72, v72
	v_add_f32_e32 v200, v200, v64
	s_waitcnt lgkmcnt(8)
	v_mfma_f32_32x32x16_bf16 v[98:113], v[176:179], v[134:137], v[98:113]
	ds_read2_b64 v[172:175], v242 offset0:8 offset1:10
	ds_read2_b64 v[176:179], v163 offset0:40 offset1:42
	v_exp_f32_e32 v73, v73
	v_add_f32_e32 v201, v201, v65
	v_cvt_pk_bf16_f32 v224, v66, v67
	v_cvt_pk_bf16_f32 v225, v68, v69
	v_cvt_pk_bf16_f32 v226, v70, v71
	s_waitcnt lgkmcnt(3)
	v_mfma_f32_32x32x16_bf16 v[18:33], v[164:167], v[228:231], v[18:33]
	v_cvt_pk_bf16_f32 v227, v72, v73
	v_exp_f32_e32 v74, v74
	v_add_f32_e32 v200, v200, v66
	v_exp_f32_e32 v75, v75
	v_add_f32_e32 v201, v201, v67
	s_waitcnt lgkmcnt(2)
	v_mfma_f32_32x32x16_bf16 v[34:49], v[168:171], v[228:231], v[34:49]
	v_exp_f32_e32 v76, v76
	v_add_f32_e32 v200, v200, v68
	v_exp_f32_e32 v77, v77
	v_add_f32_e32 v201, v201, v69
	v_exp_f32_e32 v78, v78
	s_waitcnt lgkmcnt(9)
	v_mfma_f32_32x32x16_bf16 v[82:97], v[180:183], v[138:141], v[82:97]
	v_add_f32_e32 v200, v200, v70
	v_exp_f32_e32 v79, v79
	v_add_f32_e32 v201, v201, v71
	v_exp_f32_e32 v80, v80
	v_add_f32_e32 v200, v200, v72
	s_waitcnt lgkmcnt(8)
	v_mfma_f32_32x32x16_bf16 v[98:113], v[184:187], v[138:141], v[98:113]
	ds_read2_b64 v[180:183], v242 offset0:12 offset1:14
	ds_read2_b64 v[184:187], v163 offset0:44 offset1:46
	v_exp_f32_e32 v81, v81
	v_add_f32_e32 v201, v201, v73
	v_cvt_pk_bf16_f32 v228, v74, v75
	v_cvt_pk_bf16_f32 v229, v76, v77
	v_cvt_pk_bf16_f32 v230, v78, v79
	s_waitcnt lgkmcnt(3)
	v_mfma_f32_32x32x16_bf16 v[18:33], v[172:175], v[224:227], v[18:33]
	v_cvt_pk_bf16_f32 v231, v80, v81
	v_add_f32_e32 v200, v200, v74
	v_add_f32_e32 v201, v201, v75
	v_add_f32_e32 v200, v200, v76
	v_add_f32_e32 v201, v201, v77
	v_add_f32_e32 v200, v200, v78
	v_add_f32_e32 v201, v201, v79
	v_add_f32_e32 v200, v200, v80
	s_waitcnt lgkmcnt(2)
	v_mfma_f32_32x32x16_bf16 v[34:49], v[176:179], v[224:227], v[34:49]
	v_add_f32_e32 v201, v201, v81
	v_add_f32_e32 v200, v200, v201
	v_add_f32_e32 v162, v162, v200
	s_waitcnt lgkmcnt(9)
	v_mfma_f32_32x32x16_bf16 v[82:97], v[188:191], v[142:145], v[82:97]
	s_waitcnt lgkmcnt(8)
	v_mfma_f32_32x32x16_bf16 v[98:113], v[192:195], v[142:145], v[98:113]
	s_waitcnt lgkmcnt(7)
	v_mfma_f32_32x32x16_bf16 v[82:97], v[196:199], v[146:149], v[82:97]
	s_waitcnt lgkmcnt(6)
	v_mfma_f32_32x32x16_bf16 v[98:113], v[220:223], v[146:149], v[98:113]
	s_waitcnt lgkmcnt(0)
	v_cndmask_b32_e64 v0, 0, 1, s[44:45]
	v_cmp_ne_u32_e64 s[42:43], 1, v0
	s_andn2_b64 vcc, exec, s[44:45]
	s_cbranch_vccnz .Lt1a_mid
	s_and_b32 s44, s53, 2
	s_mulk_i32 s44, 0x3400
	s_add_i32 s62, s44, 0
	v_add_u32_e32 v0, s62, v151
	ds_write_b128 v0, v[118:121]
	s_and_saveexec_b64 s[44:45], s[40:41]
	v_add_u32_e32 v0, s62, v159
	ds_write_b128 v0, v[6:9]
	s_or_b64 exec, exec, s[44:45]
.Lt1a_mid:
	s_add_i32 s62, s52, 1
	s_cmp_lt_u32 s62, s48
	s_cselect_b64 s[44:45], -1, 0
	s_cmp_ge_u32 s62, s48
	s_cbranch_scc1 .Lt1a_end
	s_addk_i32 s61, 0x2200
	s_cmp_lg_u32 s25, 2
	s_cselect_b32 s61, s61, 0
	v_add_u32_e32 v0, s61, v158
	v_add_u32_e32 v0, 0xd000, v0
	ds_write2_b64 v0, v[130:131], v[132:133] offset1:1

.LBB0_556:
	s_add_i32 s61, s25, 1
	s_cmp_lg_u32 s25, 2
	s_cselect_b32 s25, s61, 0
	s_andn2_b64 vcc, exec, s[44:45]
	s_waitcnt lgkmcnt(0)
	s_barrier
	s_cbranch_vccnz .LBB0_572
	s_cmp_ge_u32 s52, s51
	s_cbranch_scc1 .Lh2_skip
	s_andn2_b32 s62, 2, s52
	s_mulk_i32 s62, 0x3400
	v_add_u32_e32 v0, s62, v160
	s_mul_i32 s62, s25, 0x2200
	v_add_u32_e32 v242, s62, v161
	v_add_u32_e32 v163, 0xe000, v242
	v_add_u32_e32 v242, 0xd000, v242
	ds_read_b128 v[50:53], v0 offset:0
	ds_read_b128 v[66:69], v0 offset:6656
	ds_read_b128 v[164:167], v0 offset:32
	ds_read_b128 v[168:171], v0 offset:6688
	ds_read2_b64 v[238:241], v242 offset0:0 offset1:2
	ds_read2_b64 v[234:237], v163 offset0:32 offset1:34
	ds_read_b128 v[172:175], v0 offset:64
	ds_read_b128 v[176:179], v0 offset:6720
	ds_read_b128 v[180:183], v0 offset:96
	ds_read_b128 v[184:187], v0 offset:6752
	ds_read_b128 v[188:191], v0 offset:128
	ds_read_b128 v[192:195], v0 offset:6784
	ds_read_b128 v[196:199], v0 offset:160
	ds_read_b128 v[220:223], v0 offset:6816
	v_exp_f32_e32 v82, v82
	v_exp_f32_e32 v83, v83
	v_exp_f32_e32 v84, v84
	v_exp_f32_e32 v85, v85
	v_exp_f32_e32 v86, v86
	v_exp_f32_e32 v87, v87
	v_exp_f32_e32 v88, v88
	v_exp_f32_e32 v89, v89
	s_waitcnt lgkmcnt(13)
	v_mfma_f32_32x32x16_bf16 v[50:65], v[50:53], v[122:125], 0
	v_cvt_pk_bf16_f32 v224, v82, v83
	v_cvt_pk_bf16_f32 v225, v84, v85
	v_cvt_pk_bf16_f32 v226, v86, v87
	v_cvt_pk_bf16_f32 v227, v88, v89
	v_exp_f32_e32 v90, v90
	v_add_f32_e32 v200, v82, v83
	s_waitcnt lgkmcnt(12)
	v_mfma_f32_32x32x16_bf16 v[66:81], v[66:69], v[122:125], 0
	v_exp_f32_e32 v91, v91
	v_exp_f32_e32 v92, v92
	v_add_f32_e32 v201, v84, v85
	v_exp_f32_e32 v93, v93
	s_waitcnt vmcnt(0)
	s_cmp_ge_u32 s52, s5
	s_cbranch_scc1 .Lp2a_561
	s_waitcnt vmcnt(0)
	v_lshl_add_u64 v[118:119], s[54:55], 0, v[154:155]
	v_add_co_u32_e32 v118, vcc, 0xbe0c000, v118
	s_nop 1
	v_addc_co_u32_e32 v119, vcc, 0, v119, vcc
	global_load_dwordx4 v[118:121], v[118:119], off
	s_and_saveexec_b64 s[44:45], s[40:41]
	s_cbranch_execz .Lp2a_560
	v_lshl_add_u64 v[6:7], s[54:55], 0, v[152:153]
	v_add_co_u32_e32 v6, vcc, 0xbe0c000, v6
	s_nop 1
	v_addc_co_u32_e32 v7, vcc, 0, v7, vcc
	global_load_dwordx4 v[6:9], v[6:7], off

.Lp2a_end:
	s_waitcnt lgkmcnt(11)
	v_mfma_f32_32x32x16_bf16 v[50:65], v[164:167], v[126:129], v[50:65]
	v_exp_f32_e32 v94, v94
	v_add_f32_e32 v200, v200, v86
	v_exp_f32_e32 v95, v95
	v_add_f32_e32 v201, v201, v87
	v_exp_f32_e32 v96, v96
	s_waitcnt lgkmcnt(10)
	v_mfma_f32_32x32x16_bf16 v[66:81], v[168:171], v[126:129], v[66:81]
	ds_read2_b64 v[164:167], v242 offset0:4 offset1:6
	ds_read2_b64 v[168:171], v163 offset0:36 offset1:38
	v_add_f32_e32 v200, v200, v88
	v_exp_f32_e32 v97, v97
	v_add_f32_e32 v201, v201, v89
	v_cvt_pk_bf16_f32 v228, v90, v91
	v_cvt_pk_bf16_f32 v229, v92, v93
	s_waitcnt lgkmcnt(11)
	v_mfma_f32_32x32x16_bf16 v[18:33], v[238:241], v[224:227], v[18:33]
	v_cvt_pk_bf16_f32 v230, v94, v95
	v_cvt_pk_bf16_f32 v231, v96, v97
	v_exp_f32_e32 v98, v98
	v_add_f32_e32 v200, v200, v90
	v_exp_f32_e32 v99, v99
	v_add_f32_e32 v201, v201, v91
	s_waitcnt lgkmcnt(10)
	v_mfma_f32_32x32x16_bf16 v[34:49], v[234:237], v[224:227], v[34:49]
	v_exp_f32_e32 v100, v100
	v_add_f32_e32 v200, v200, v92
	v_exp_f32_e32 v101, v101
	v_add_f32_e32 v201, v201, v93
	v_exp_f32_e32 v102, v102
	s_waitcnt lgkmcnt(9)
	v_mfma_f32_32x32x16_bf16 v[50:65], v[172:175], v[134:137], v[50:65]
	v_add_f32_e32 v200, v200, v94
	v_exp_f32_e32 v103, v103
	v_add_f32_e32 v201, v201, v95
	v_exp_f32_e32 v104, v104
	v_add_f32_e32 v200, v200, v96
	s_waitcnt lgkmcnt(8)
	v_mfma_f32_32x32x16_bf16 v[66:81], v[176:179], v[134:137], v[66:81]
	ds_read2_b64 v[172:175], v242 offset0:8 offset1:10
	ds_read2_b64 v[176:179], v163 offset0:40 offset1:42
	v_exp_f32_e32 v105, v105
	v_add_f32_e32 v201, v201, v97
	v_cvt_pk_bf16_f32 v224, v98, v99
	v_cvt_pk_bf16_f32 v225, v100, v101
	v_cvt_pk_bf16_f32 v226, v102, v103
	s_waitcnt lgkmcnt(3)
	v_mfma_f32_32x32x16_bf16 v[18:33], v[164:167], v[228:231], v[18:33]
	v_cvt_pk_bf16_f32 v227, v104, v105
	v_exp_f32_e32 v106, v106
	v_add_f32_e32 v200, v200, v98
	v_exp_f32_e32 v107, v107
	v_add_f32_e32 v201, v201, v99
	s_waitcnt lgkmcnt(2)
	v_mfma_f32_32x32x16_bf16 v[34:49], v[168:171], v[228:231], v[34:49]
	v_exp_f32_e32 v108, v108
	v_add_f32_e32 v200, v200, v100
	v_exp_f32_e32 v109, v109
	v_add_f32_e32 v201, v201, v101
	v_exp_f32_e32 v110, v110
	s_waitcnt lgkmcnt(9)
	v_mfma_f32_32x32x16_bf16 v[50:65], v[180:183], v[138:141], v[50:65]
	v_add_f32_e32 v200, v200, v102
	v_exp_f32_e32 v111, v111
	v_add_f32_e32 v201, v201, v103
	v_exp_f32_e32 v112, v112
	v_add_f32_e32 v200, v200, v104
	s_waitcnt lgkmcnt(8)
	v_mfma_f32_32x32x16_bf16 v[66:81], v[184:187], v[138:141], v[66:81]
	ds_read2_b64 v[180:183], v242 offset0:12 offset1:14
	ds_read2_b64 v[184:187], v163 offset0:44 offset1:46
	v_exp_f32_e32 v113, v113
	v_add_f32_e32 v201, v201, v105
	v_cvt_pk_bf16_f32 v228, v106, v107
	v_cvt_pk_bf16_f32 v229, v108, v109
	v_cvt_pk_bf16_f32 v230, v110, v111
	s_waitcnt lgkmcnt(3)
	v_mfma_f32_32x32x16_bf16 v[18:33], v[172:175], v[224:227], v[18:33]
	v_cvt_pk_bf16_f32 v231, v112, v113
	v_add_f32_e32 v200, v200, v106
	v_add_f32_e32 v201, v201, v107
	v_add_f32_e32 v200, v200, v108
	v_add_f32_e32 v201, v201, v109
	v_add_f32_e32 v200, v200, v110
	v_add_f32_e32 v201, v201, v111
	v_add_f32_e32 v200, v200, v112
	s_waitcnt lgkmcnt(2)
	v_mfma_f32_32x32x16_bf16 v[34:49], v[176:179], v[224:227], v[34:49]
	v_add_f32_e32 v201, v201, v113
	v_add_f32_e32 v200, v200, v201
	v_add_f32_e32 v162, v162, v200
	s_waitcnt lgkmcnt(9)
	v_mfma_f32_32x32x16_bf16 v[50:65], v[188:191], v[142:145], v[50:65]
	s_waitcnt lgkmcnt(8)
	v_mfma_f32_32x32x16_bf16 v[66:81], v[192:195], v[142:145], v[66:81]
	s_waitcnt lgkmcnt(7)
	v_mfma_f32_32x32x16_bf16 v[50:65], v[196:199], v[146:149], v[50:65]
	s_waitcnt lgkmcnt(6)
	v_mfma_f32_32x32x16_bf16 v[66:81], v[220:223], v[146:149], v[66:81]
	s_waitcnt lgkmcnt(0)
	s_mul_i32 s58, s25, 0x2200
	s_and_b64 vcc, exec, s[44:45]
	s_cbranch_vccnz .Lt2a_mid
	s_and_b32 s44, s60, 3
	s_mulk_i32 s44, 0x3400
	s_add_i32 s52, s44, 0
	v_add_u32_e32 v0, s52, v151
	ds_write_b128 v0, v[2:5]
	s_and_saveexec_b64 s[44:45], s[40:41]
	v_add_u32_e32 v0, s52, v159
	ds_write_b128 v0, v[10:13]
	s_or_b64 exec, exec, s[44:45]
.Lt2a_mid:
	s_and_b64 vcc, exec, s[42:43]
	s_cbranch_vccnz .Lt2a_end
	s_addk_i32 s58, 0x2200
	s_cmp_lg_u32 s25, 2
	s_cselect_b32 s42, s58, 0
	v_add_u32_e32 v0, s42, v158
	v_add_u32_e32 v0, 0xd000, v0
	ds_write2_b64 v0, v[114:115], v[116:117] offset1:1
